# v12 + P3/P12 main loops: LDS-DMA loads use the SGPR-base + 32-bit VGPR offset form (no per-load 64-bit VALU address add)
# speedup vs baseline: 1.0055x; 1.0034x over previous
; #define PG8_STAGE(bufoff, gbase, voff) do { _Pragma("unroll") for (int _i = 0; _i < 2; ++_i) \
;         __builtin_amdgcn_global_load_lds((const unsigned*)((const char*)(gbase) + (voff)[_i]), (PG8_LAS unsigned*)(lds + (bufoff) + ldsw + _i * 8192), 16, 0, 0); } while (0)
; #define PG8_LDA(dst, b, h) do { _Pragma("unroll") for (int m = 0; m < 4; ++m) _Pragma("unroll") for (int k = 0; k < 2; ++k) dst[m][k] = *(const PG8_LAS bf16x8*)(lds + PG8_SA(b, h) + aoff + m * 2048 + k * 1024); } while (0)
; #define PG8_LDB(dst, b, h) do { _Pragma("unroll") for (int n = 0; n < 2; ++n) _Pragma("unroll") for (int k = 0; k < 2; ++k) dst[n][k] = *(const PG8_LAS bf16x8*)(lds + PG8_SB(b, h) + boff + n * 2048 + k * 1024); } while (0)
; #define PG8_WAIT_V(n) asm volatile("s_waitcnt vmcnt(" #n ")" ::: "memory")
; #define PG8_WAIT_L(n) asm volatile("s_waitcnt lgkmcnt(" #n ")" ::: "memory")
; #define PG8_BAR __builtin_amdgcn_s_barrier()
; #define PG8_SCHED __builtin_amdgcn_sched_barrier(0)
; #define PG8_BAR __builtin_amdgcn_s_barrier()
; template <class Epi, class Sched, bool ALIGN_EPI = false>
; __device__ __forceinline__ void gemm_phase8(PG8_LAS unsigned char* lds, const Gemm g, const Sched& S, const Epi& E) {
;     ...
;         for (int t = 0; t < nt; t += 2) {
;             const bool last = (t == nt - 2);
;             const char* a1 = cA + (size_t)(t + 1) * kstep;
;             const char* a2 = last ? nA : cA + (size_t)(t + 2) * kstep; const char* b2 = last ? nB : cB + (size_t)(t + 2) * kstep;
;             const char* a3 = a2 + kstep; const char* b3 = b2 + kstep;
;             if (last && has_next) S.a_ready(nxt);
;             PG8_LDB(B0, 0, 0); PG8_LDB(B1, 0, 1); PG8_SCHED; PG8_LDA(At, 0, 0); PG8_STAGE(PG8_SA(1, 1), a1 + hstepA, voffA);
;             PG8_WAIT_V(8); PG8_WAIT_L(0); PG8_BAR; PG8_MMA(0, 0, At, B0); PG8_MMA(0, 1, At, B1); PG8_BAR; PG8_SCHED;
;             PG8_LDA(At, 0, 1); PG8_STAGE(PG8_SB(0, 0), b2, voffB); PG8_STAGE(PG8_SB(0, 1), b2 + hstepB, voffB); PG8_STAGE(PG8_SA(0, 0), a2, voffA);
;             PG8_WAIT_V(8); PG8_WAIT_L(0); PG8_BAR; PG8_MMA(1, 0, At, B0); PG8_MMA(1, 1, At, B1); PG8_BAR; PG8_SCHED;
;             PG8_LDB(B0, 1, 0); PG8_LDB(B1, 1, 1); PG8_SCHED; PG8_LDA(At, 1, 0); PG8_STAGE(PG8_SA(0, 1), a2 + hstepA, voffA);
;             PG8_WAIT_V(8); PG8_WAIT_L(0); PG8_BAR; PG8_MMA(0, 0, At, B0); PG8_MMA(0, 1, At, B1); PG8_BAR; PG8_SCHED;
.LBB0_325:
	ds_read_b128 v[18:21], v191
	ds_read_b128 v[26:29], v191 offset:2048
	ds_read_b128 v[22:25], v192
	ds_read_b128 v[30:33], v192 offset:2048
	ds_read_b128 v[2:5], v193
	ds_read_b128 v[10:13], v193 offset:2048
	ds_read_b128 v[6:9], v194
	ds_read_b128 v[14:17], v194 offset:2048
	s_add_u32 s24, s22, 0xfffc0080
	s_addc_u32 s25, s23, -1
	s_cmp_eq_u32 s65, 12
	s_cselect_b32 s27, s15, s25
	s_cselect_b32 s26, s61, s24
	s_cselect_b32 s25, s13, s64
	s_cselect_b32 s24, s62, s63
	s_add_i32 m0, s21, 0xc000
	ds_read_b128 v[178:181], v195
	ds_read_b128 v[198:201], v195 offset:2048
	ds_read_b128 v[182:185], v196
	ds_read_b128 v[202:205], v196 offset:2048
	ds_read_b128 v[206:209], v195 offset:4096
	ds_read_b128 v[214:217], v195 offset:6144
	ds_read_b128 v[210:213], v196 offset:4096
	ds_read_b128 v[218:221], v196 offset:6144
	global_load_lds_dwordx4 v170, s[22:23]
	s_add_i32 m0, s21, 0xe000
	s_nop 0
	global_load_lds_dwordx4 v172, s[22:23]
	s_waitcnt vmcnt(8)
	s_waitcnt lgkmcnt(0)
	s_barrier
	s_setprio 1
	s_waitcnt lgkmcnt(0)
	s_cmp_eq_u32 s100, 1
	s_cbranch_scc1 .Lcy0_0f
	v_mfma_scale_f32_16x16x128_f8f6f4 v[158:161], v[18:25], v[178:185], v[158:161], v1, v186 op_sel_hi:[0,0,0]
	v_mfma_scale_f32_16x16x128_f8f6f4 v[150:153], v[26:33], v[178:185], v[150:153], v1, v186 op_sel_hi:[0,0,0]
	v_mfma_scale_f32_16x16x128_f8f6f4 v[142:145], v[18:25], v[198:205], v[142:145], v1, v186 op_sel_hi:[0,0,0]
	v_mfma_scale_f32_16x16x128_f8f6f4 v[134:137], v[26:33], v[198:205], v[134:137], v1, v186 op_sel_hi:[0,0,0]
	v_mfma_scale_f32_16x16x128_f8f6f4 v[126:129], v[18:25], v[206:213], v[126:129], v1, v186 op_sel_hi:[0,0,0]
	v_mfma_scale_f32_16x16x128_f8f6f4 v[118:121], v[26:33], v[206:213], v[118:121], v1, v186 op_sel_hi:[0,0,0]
	v_mfma_scale_f32_16x16x128_f8f6f4 v[110:113], v[18:25], v[214:221], v[110:113], v1, v186 op_sel_hi:[0,0,0]
	v_mfma_scale_f32_16x16x128_f8f6f4 v[102:105], v[26:33], v[214:221], v[102:105], v1, v186 op_sel_hi:[0,0,0]
	s_setprio 0
	s_setprio 1
	v_mfma_scale_f32_16x16x128_f8f6f4 v[154:157], v[2:9], v[178:185], v[154:157], v1, v186 op_sel_hi:[0,0,0]
	v_mfma_scale_f32_16x16x128_f8f6f4 v[146:149], v[10:17], v[178:185], v[146:149], v1, v186 op_sel_hi:[0,0,0]
	v_mfma_scale_f32_16x16x128_f8f6f4 v[138:141], v[2:9], v[198:205], v[138:141], v1, v186 op_sel_hi:[0,0,0]
	v_mfma_scale_f32_16x16x128_f8f6f4 v[130:133], v[10:17], v[198:205], v[130:133], v1, v186 op_sel_hi:[0,0,0]
	v_mfma_scale_f32_16x16x128_f8f6f4 v[122:125], v[2:9], v[206:213], v[122:125], v1, v186 op_sel_hi:[0,0,0]
	v_mfma_scale_f32_16x16x128_f8f6f4 v[114:117], v[10:17], v[206:213], v[114:117], v1, v186 op_sel_hi:[0,0,0]
	v_mfma_scale_f32_16x16x128_f8f6f4 v[106:109], v[2:9], v[214:221], v[106:109], v1, v186 op_sel_hi:[0,0,0]
	v_mfma_scale_f32_16x16x128_f8f6f4 v[98:101], v[10:17], v[214:221], v[98:101], v1, v186 op_sel_hi:[0,0,0]
.Lcy0_0j:
	s_setprio 0
	s_barrier
	s_add_i32 s66, s57, s30
	s_mov_b32 m0, s66
	ds_read_b128 v[198:201], v195 offset:16384
	ds_read_b128 v[206:209], v195 offset:18432
	ds_read_b128 v[202:205], v196 offset:16384
	ds_read_b128 v[210:213], v196 offset:18432
	ds_read_b128 v[214:217], v195 offset:20480
	ds_read_b128 v[222:225], v195 offset:22528
	ds_read_b128 v[218:221], v196 offset:20480
	ds_read_b128 v[226:229], v196 offset:22528
	global_load_lds_dwordx4 v164, s[24:25]
	s_add_i32 m0, s66, 0x2000
	s_add_u32 s66, s24, 0x40000
	s_addc_u32 s67, s25, 0
	s_add_i32 s72, s58, s30
	global_load_lds_dwordx4 v168, s[24:25]
	s_mov_b32 m0, s72
	s_nop 0
	global_load_lds_dwordx4 v164, s[66:67]
	s_add_i32 m0, s72, 0x2000
	s_nop 0
	global_load_lds_dwordx4 v168, s[66:67]
	s_mov_b32 m0, s21
	s_nop 0
	global_load_lds_dwordx4 v162, s[26:27]
	s_mov_b32 m0, s34
	s_nop 0
	global_load_lds_dwordx4 v166, s[26:27]
	s_waitcnt vmcnt(8)
	s_waitcnt lgkmcnt(0)
	s_barrier
	s_setprio 1
	s_waitcnt lgkmcnt(0)
	s_cmp_eq_u32 s100, 1
	s_cbranch_scc1 .Lcy0_1f
	v_mfma_scale_f32_16x16x128_f8f6f4 v[94:97], v[18:25], v[198:205], v[94:97], v1, v186 op_sel_hi:[0,0,0]
	v_mfma_scale_f32_16x16x128_f8f6f4 v[86:89], v[26:33], v[198:205], v[86:89], v1, v186 op_sel_hi:[0,0,0]
	v_mfma_scale_f32_16x16x128_f8f6f4 v[78:81], v[18:25], v[206:213], v[78:81], v1, v186 op_sel_hi:[0,0,0]
	v_mfma_scale_f32_16x16x128_f8f6f4 v[70:73], v[26:33], v[206:213], v[70:73], v1, v186 op_sel_hi:[0,0,0]
	v_mfma_scale_f32_16x16x128_f8f6f4 v[62:65], v[18:25], v[214:221], v[62:65], v1, v186 op_sel_hi:[0,0,0]
	v_mfma_scale_f32_16x16x128_f8f6f4 v[54:57], v[26:33], v[214:221], v[54:57], v1, v186 op_sel_hi:[0,0,0]
	v_mfma_scale_f32_16x16x128_f8f6f4 v[46:49], v[18:25], v[222:229], v[46:49], v1, v186 op_sel_hi:[0,0,0]
	v_mfma_scale_f32_16x16x128_f8f6f4 v[38:41], v[26:33], v[222:229], v[38:41], v1, v186 op_sel_hi:[0,0,0]
	s_setprio 0
	s_setprio 1
	v_mfma_scale_f32_16x16x128_f8f6f4 v[90:93], v[2:9], v[198:205], v[90:93], v1, v186 op_sel_hi:[0,0,0]
	v_mfma_scale_f32_16x16x128_f8f6f4 v[82:85], v[10:17], v[198:205], v[82:85], v1, v186 op_sel_hi:[0,0,0]
	v_mfma_scale_f32_16x16x128_f8f6f4 v[74:77], v[2:9], v[206:213], v[74:77], v1, v186 op_sel_hi:[0,0,0]
	v_mfma_scale_f32_16x16x128_f8f6f4 v[66:69], v[10:17], v[206:213], v[66:69], v1, v186 op_sel_hi:[0,0,0]
	v_mfma_scale_f32_16x16x128_f8f6f4 v[58:61], v[2:9], v[214:221], v[58:61], v1, v186 op_sel_hi:[0,0,0]
	v_mfma_scale_f32_16x16x128_f8f6f4 v[50:53], v[10:17], v[214:221], v[50:53], v1, v186 op_sel_hi:[0,0,0]
	v_mfma_scale_f32_16x16x128_f8f6f4 v[42:45], v[2:9], v[222:229], v[42:45], v1, v186 op_sel_hi:[0,0,0]
	v_mfma_scale_f32_16x16x128_f8f6f4 v[34:37], v[10:17], v[222:229], v[34:37], v1, v186 op_sel_hi:[0,0,0]
; #define PG8_STAGE(bufoff, gbase, voff) do { _Pragma("unroll") for (int _i = 0; _i < 2; ++_i) \
;         __builtin_amdgcn_global_load_lds((const unsigned*)((const char*)(gbase) + (voff)[_i]), (PG8_LAS unsigned*)(lds + (bufoff) + ldsw + _i * 8192), 16, 0, 0); } while (0)
; #define PG8_LDA(dst, b, h) do { _Pragma("unroll") for (int m = 0; m < 4; ++m) _Pragma("unroll") for (int k = 0; k < 2; ++k) dst[m][k] = *(const PG8_LAS bf16x8*)(lds + PG8_SA(b, h) + aoff + m * 2048 + k * 1024); } while (0)
; #define PG8_LDB(dst, b, h) do { _Pragma("unroll") for (int n = 0; n < 2; ++n) _Pragma("unroll") for (int k = 0; k < 2; ++k) dst[n][k] = *(const PG8_LAS bf16x8*)(lds + PG8_SB(b, h) + boff + n * 2048 + k * 1024); } while (0)
; #define PG8_MMA(ai, bj, At, Bt) do { __builtin_amdgcn_s_setprio(1); _Pragma("unroll") for (int m = 0; m < 4; ++m) _Pragma("unroll") for (int n = 0; n < 2; ++n) _Pragma("unroll") for (int k = 0; k < 2; ++k) \
;         acc[ai][bj][m][n] = __builtin_amdgcn_mfma_f32_16x16x32_bf16(Bt[n][k], At[m][k], acc[ai][bj][m][n], 0, 0, 0); __builtin_amdgcn_s_setprio(0); } while (0)
; #define PG8_WAIT_V(n) asm volatile("s_waitcnt vmcnt(" #n ")" ::: "memory")
; #define PG8_WAIT_L(n) asm volatile("s_waitcnt lgkmcnt(" #n ")" ::: "memory")
; #define PG8_BAR __builtin_amdgcn_s_barrier()
; #define PG8_SCHED __builtin_amdgcn_sched_barrier(0)
; #define PG8_STAGE(bufoff, gbase, voff) do { _Pragma("unroll") for (int _i = 0; _i < 2; ++_i) \
;         __builtin_amdgcn_global_load_lds((const unsigned*)((const char*)(gbase) + (voff)[_i]), (PG8_LAS unsigned*)(lds + (bufoff) + ldsw + _i * 8192), 16, 0, 0); } while (0)
; #define PG8_BAR __builtin_amdgcn_s_barrier()
; template <class Epi, class Sched, bool ALIGN_EPI = false>
; __device__ __forceinline__ void gemm_phase8(PG8_LAS unsigned char* lds, const Gemm g, const Sched& S, const Epi& E) {
;     ...
;             PG8_LDB(B0, 1, 0); PG8_LDB(B1, 1, 1); PG8_SCHED; PG8_LDA(At, 1, 0); PG8_STAGE(PG8_SA(0, 1), a2 + hstepA, voffA);
;             PG8_WAIT_V(8); PG8_WAIT_L(0); PG8_BAR; PG8_MMA(0, 0, At, B0); PG8_MMA(0, 1, At, B1); PG8_BAR; PG8_SCHED;
;             PG8_LDA(At, 1, 1); PG8_STAGE(PG8_SB(1, 0), b3, voffB); PG8_STAGE(PG8_SB(1, 1), b3 + hstepB, voffB); PG8_STAGE(PG8_SA(1, 0), a3, voffA);
;             PG8_WAIT_V(8); PG8_WAIT_L(0); PG8_BAR; PG8_MMA(1, 0, At, B0); PG8_MMA(1, 1, At, B1); PG8_BAR; PG8_SCHED;
;         }
.Lcy0_1j:
	s_setprio 0
	s_barrier
	s_add_i32 s66, 0, 0x18000
	s_add_i32 s67, 0, 0x1c000
	v_add_u32_e32 v6, s66, v187
	v_add_u32_e32 v14, s66, v188
	v_add_u32_e32 v22, s67, v187
	v_add_u32_e32 v30, s67, v188
	ds_read_b128 v[2:5], v6
	ds_read_b128 v[10:13], v6 offset:2048
	ds_read_b128 v[6:9], v14
	ds_read_b128 v[14:17], v14 offset:2048
	ds_read_b128 v[18:21], v22
	ds_read_b128 v[26:29], v22 offset:2048
	ds_read_b128 v[22:25], v30
	ds_read_b128 v[30:33], v30 offset:2048
	s_add_u32 s26, s26, 0x40000
	s_addc_u32 s27, s27, 0
	s_mov_b32 m0, s35
	ds_read_b128 v[198:201], v195 offset:32768
	ds_read_b128 v[206:209], v195 offset:34816
	ds_read_b128 v[202:205], v196 offset:32768
	ds_read_b128 v[210:213], v196 offset:34816
	ds_read_b128 v[214:217], v195 offset:36864
	ds_read_b128 v[222:225], v195 offset:38912
	ds_read_b128 v[218:221], v196 offset:36864
	ds_read_b128 v[226:229], v196 offset:38912
	global_load_lds_dwordx4 v162, s[26:27]
	s_mov_b32 m0, s52
	s_nop 0
	global_load_lds_dwordx4 v166, s[26:27]
	s_waitcnt vmcnt(8)
	s_waitcnt lgkmcnt(0)
	s_barrier
	s_setprio 1
	s_waitcnt lgkmcnt(0)
	v_mfma_scale_f32_16x16x128_f8f6f4 v[158:161], v[2:9], v[198:205], v[158:161], v1, v186 op_sel_hi:[0,0,0]
	v_mfma_scale_f32_16x16x128_f8f6f4 v[150:153], v[10:17], v[198:205], v[150:153], v1, v186 op_sel_hi:[0,0,0]
	v_mfma_scale_f32_16x16x128_f8f6f4 v[142:145], v[2:9], v[206:213], v[142:145], v1, v186 op_sel_hi:[0,0,0]
	v_mfma_scale_f32_16x16x128_f8f6f4 v[134:137], v[10:17], v[206:213], v[134:137], v1, v186 op_sel_hi:[0,0,0]
	v_mfma_scale_f32_16x16x128_f8f6f4 v[126:129], v[2:9], v[214:221], v[126:129], v1, v186 op_sel_hi:[0,0,0]
	v_mfma_scale_f32_16x16x128_f8f6f4 v[118:121], v[10:17], v[214:221], v[118:121], v1, v186 op_sel_hi:[0,0,0]
	v_mfma_scale_f32_16x16x128_f8f6f4 v[110:113], v[2:9], v[222:229], v[110:113], v1, v186 op_sel_hi:[0,0,0]
	v_mfma_scale_f32_16x16x128_f8f6f4 v[102:105], v[10:17], v[222:229], v[102:105], v1, v186 op_sel_hi:[0,0,0]
	s_setprio 0
	s_setprio 1
	v_mfma_scale_f32_16x16x128_f8f6f4 v[154:157], v[18:25], v[198:205], v[154:157], v1, v186 op_sel_hi:[0,0,0]
	v_mfma_scale_f32_16x16x128_f8f6f4 v[146:149], v[26:33], v[198:205], v[146:149], v1, v186 op_sel_hi:[0,0,0]
	v_mfma_scale_f32_16x16x128_f8f6f4 v[138:141], v[18:25], v[206:213], v[138:141], v1, v186 op_sel_hi:[0,0,0]
	v_mfma_scale_f32_16x16x128_f8f6f4 v[130:133], v[26:33], v[206:213], v[130:133], v1, v186 op_sel_hi:[0,0,0]
	v_mfma_scale_f32_16x16x128_f8f6f4 v[122:125], v[18:25], v[214:221], v[122:125], v1, v186 op_sel_hi:[0,0,0]
	v_mfma_scale_f32_16x16x128_f8f6f4 v[114:117], v[26:33], v[214:221], v[114:117], v1, v186 op_sel_hi:[0,0,0]
	v_mfma_scale_f32_16x16x128_f8f6f4 v[106:109], v[18:25], v[222:229], v[106:109], v1, v186 op_sel_hi:[0,0,0]
	v_mfma_scale_f32_16x16x128_f8f6f4 v[98:101], v[26:33], v[222:229], v[98:101], v1, v186 op_sel_hi:[0,0,0]
	s_setprio 0
	s_barrier
	s_add_i32 s101, s66, s30
	s_add_u32 s98, s24, s8
	s_addc_u32 s99, s25, s9
	s_mov_b32 m0, s101
	ds_read_b128 v[198:201], v195 offset:49152
	ds_read_b128 v[206:209], v195 offset:51200
	ds_read_b128 v[202:205], v196 offset:49152
	ds_read_b128 v[210:213], v196 offset:51200
	ds_read_b128 v[214:217], v195 offset:53248
	ds_read_b128 v[222:225], v195 offset:55296
	ds_read_b128 v[218:221], v196 offset:53248
	ds_read_b128 v[226:229], v196 offset:55296
	global_load_lds_dwordx4 v164, s[98:99]
	s_add_i32 m0, s101, 0x2000
	s_add_u32 s24, s24, 0x40080
	s_addc_u32 s25, s25, 0
	s_add_i32 s101, s67, s30
	global_load_lds_dwordx4 v168, s[98:99]
	s_add_u32 s98, s26, s8
	s_addc_u32 s99, s27, s9
	s_sub_u32 s98, s98, 0x40000
	s_subb_u32 s99, s99, 0
	s_mov_b32 m0, s101
	s_nop 0
	global_load_lds_dwordx4 v164, s[24:25]
	s_add_i32 m0, s101, 0x2000
	s_nop 0
	global_load_lds_dwordx4 v168, s[24:25]
	s_mov_b32 m0, s55
	s_nop 0
	global_load_lds_dwordx4 v162, s[98:99]
	s_mov_b32 m0, s56
	s_nop 0
	global_load_lds_dwordx4 v166, s[98:99]
	s_waitcnt vmcnt(8)
	s_waitcnt lgkmcnt(0)
	s_barrier
	s_setprio 1
	s_waitcnt lgkmcnt(0)
	v_mfma_scale_f32_16x16x128_f8f6f4 v[94:97], v[2:9], v[198:205], v[94:97], v1, v186 op_sel_hi:[0,0,0]
	v_mfma_scale_f32_16x16x128_f8f6f4 v[86:89], v[10:17], v[198:205], v[86:89], v1, v186 op_sel_hi:[0,0,0]
	v_mfma_scale_f32_16x16x128_f8f6f4 v[78:81], v[2:9], v[206:213], v[78:81], v1, v186 op_sel_hi:[0,0,0]
	v_mfma_scale_f32_16x16x128_f8f6f4 v[70:73], v[10:17], v[206:213], v[70:73], v1, v186 op_sel_hi:[0,0,0]
	v_mfma_scale_f32_16x16x128_f8f6f4 v[62:65], v[2:9], v[214:221], v[62:65], v1, v186 op_sel_hi:[0,0,0]
	v_mfma_scale_f32_16x16x128_f8f6f4 v[54:57], v[10:17], v[214:221], v[54:57], v1, v186 op_sel_hi:[0,0,0]
	v_mfma_scale_f32_16x16x128_f8f6f4 v[46:49], v[2:9], v[222:229], v[46:49], v1, v186 op_sel_hi:[0,0,0]
	v_mfma_scale_f32_16x16x128_f8f6f4 v[38:41], v[10:17], v[222:229], v[38:41], v1, v186 op_sel_hi:[0,0,0]
	s_setprio 0
	s_setprio 1
	v_mfma_scale_f32_16x16x128_f8f6f4 v[90:93], v[18:25], v[198:205], v[90:93], v1, v186 op_sel_hi:[0,0,0]
	v_mfma_scale_f32_16x16x128_f8f6f4 v[82:85], v[26:33], v[198:205], v[82:85], v1, v186 op_sel_hi:[0,0,0]
	v_mfma_scale_f32_16x16x128_f8f6f4 v[74:77], v[18:25], v[206:213], v[74:77], v1, v186 op_sel_hi:[0,0,0]
	v_mfma_scale_f32_16x16x128_f8f6f4 v[66:69], v[26:33], v[206:213], v[66:69], v1, v186 op_sel_hi:[0,0,0]
	v_mfma_scale_f32_16x16x128_f8f6f4 v[58:61], v[18:25], v[214:221], v[58:61], v1, v186 op_sel_hi:[0,0,0]
	v_mfma_scale_f32_16x16x128_f8f6f4 v[50:53], v[26:33], v[214:221], v[50:53], v1, v186 op_sel_hi:[0,0,0]
	v_mfma_scale_f32_16x16x128_f8f6f4 v[42:45], v[18:25], v[222:229], v[42:45], v1, v186 op_sel_hi:[0,0,0]
	v_mfma_scale_f32_16x16x128_f8f6f4 v[34:37], v[26:33], v[222:229], v[34:37], v1, v186 op_sel_hi:[0,0,0]
	s_setprio 0
	s_barrier
	s_add_i32 s65, s65, 2
	s_add_u32 s22, s22, 0x100
	s_addc_u32 s23, s23, 0
	s_add_u32 s63, s63, 0x100
	s_addc_u32 s64, s64, 0
	s_cmp_gt_u32 s65, 13
	s_cbranch_scc0 .LBB0_325
	s_and_b64 vcc, exec, s[10:11]
	s_cbranch_vccz .LBB0_328
	s_barrier

; #define PG8_STAGE(bufoff, gbase, voff) do { _Pragma("unroll") for (int _i = 0; _i < 2; ++_i) \
;         __builtin_amdgcn_global_load_lds((const unsigned*)((const char*)(gbase) + (voff)[_i]), (PG8_LAS unsigned*)(lds + (bufoff) + ldsw + _i * 8192), 16, 0, 0); } while (0)
; #define PG8_LDA(dst, b, h) do { _Pragma("unroll") for (int m = 0; m < 4; ++m) _Pragma("unroll") for (int k = 0; k < 2; ++k) dst[m][k] = *(const PG8_LAS bf16x8*)(lds + PG8_SA(b, h) + aoff + m * 2048 + k * 1024); } while (0)
; #define PG8_LDB(dst, b, h) do { _Pragma("unroll") for (int n = 0; n < 2; ++n) _Pragma("unroll") for (int k = 0; k < 2; ++k) dst[n][k] = *(const PG8_LAS bf16x8*)(lds + PG8_SB(b, h) + boff + n * 2048 + k * 1024); } while (0)
; #define PG8_WAIT_V(n) asm volatile("s_waitcnt vmcnt(" #n ")" ::: "memory")
; #define PG8_WAIT_L(n) asm volatile("s_waitcnt lgkmcnt(" #n ")" ::: "memory")
; #define PG8_BAR __builtin_amdgcn_s_barrier()
; #define PG8_SCHED __builtin_amdgcn_sched_barrier(0)
; #define PG8_BAR __builtin_amdgcn_s_barrier()
; template <class Epi, class Sched, bool ALIGN_EPI = false>
; __device__ __forceinline__ void gemm_phase8(PG8_LAS unsigned char* lds, const Gemm g, const Sched& S, const Epi& E) {
;     ...
;         for (int t = 0; t < nt; t += 2) {
;             const bool last = (t == nt - 2);
;             const char* a1 = cA + (size_t)(t + 1) * kstep;
;             const char* a2 = last ? nA : cA + (size_t)(t + 2) * kstep; const char* b2 = last ? nB : cB + (size_t)(t + 2) * kstep;
;             const char* a3 = a2 + kstep; const char* b3 = b2 + kstep;
;             if (last && has_next) S.a_ready(nxt);
;             PG8_LDB(B0, 0, 0); PG8_LDB(B1, 0, 1); PG8_SCHED; PG8_LDA(At, 0, 0); PG8_STAGE(PG8_SA(1, 1), a1 + hstepA, voffA);
;             PG8_WAIT_V(8); PG8_WAIT_L(0); PG8_BAR; PG8_MMA(0, 0, At, B0); PG8_MMA(0, 1, At, B1); PG8_BAR; PG8_SCHED;
;             PG8_LDA(At, 0, 1); PG8_STAGE(PG8_SB(0, 0), b2, voffB); PG8_STAGE(PG8_SB(0, 1), b2 + hstepB, voffB); PG8_STAGE(PG8_SA(0, 0), a2, voffA);
;             PG8_WAIT_V(8); PG8_WAIT_L(0); PG8_BAR; PG8_MMA(1, 0, At, B0); PG8_MMA(1, 1, At, B1); PG8_BAR; PG8_SCHED;
;             PG8_LDB(B0, 1, 0); PG8_LDB(B1, 1, 1); PG8_SCHED; PG8_LDA(At, 1, 0); PG8_STAGE(PG8_SA(0, 1), a2 + hstepA, voffA);
;             PG8_WAIT_V(8); PG8_WAIT_L(0); PG8_BAR; PG8_MMA(0, 0, At, B0); PG8_MMA(0, 1, At, B1); PG8_BAR; PG8_SCHED;
.LBB0_1422:
	ds_read_b128 v[18:21], v191
	ds_read_b128 v[26:29], v191 offset:2048
	ds_read_b128 v[22:25], v192
	ds_read_b128 v[30:33], v192 offset:2048
	ds_read_b128 v[2:5], v193
	ds_read_b128 v[10:13], v193 offset:2048
	ds_read_b128 v[6:9], v194
	ds_read_b128 v[14:17], v194 offset:2048
	s_add_u32 s22, s20, 0xfffc0080
	s_addc_u32 s23, s21, -1
	s_cmp_eq_u32 s55, 12
	s_cselect_b32 s25, s13, s23
	s_cselect_b32 s24, s45, s22
	s_cselect_b32 s23, s11, s54
	s_cselect_b32 s22, s52, s53
	s_add_i32 m0, s19, 0xc000
	ds_read_b128 v[178:181], v195
	ds_read_b128 v[198:201], v195 offset:2048
	ds_read_b128 v[182:185], v196
	ds_read_b128 v[202:205], v196 offset:2048
	ds_read_b128 v[206:209], v195 offset:4096
	ds_read_b128 v[214:217], v195 offset:6144
	ds_read_b128 v[210:213], v196 offset:4096
	ds_read_b128 v[218:221], v196 offset:6144
	global_load_lds_dwordx4 v170, s[20:21]
	s_add_i32 m0, s19, 0xe000
	s_nop 0
	global_load_lds_dwordx4 v172, s[20:21]
	s_waitcnt vmcnt(8)
	s_waitcnt lgkmcnt(0)
	s_barrier
	s_setprio 1
	s_waitcnt lgkmcnt(0)
	s_cmp_eq_u32 s100, 1
	s_cbranch_scc1 .Lcy4_0f
	v_mfma_scale_f32_16x16x128_f8f6f4 v[158:161], v[18:25], v[178:185], v[158:161], v1, v186 op_sel_hi:[0,0,0]
	v_mfma_scale_f32_16x16x128_f8f6f4 v[150:153], v[26:33], v[178:185], v[150:153], v1, v186 op_sel_hi:[0,0,0]
	v_mfma_scale_f32_16x16x128_f8f6f4 v[142:145], v[18:25], v[198:205], v[142:145], v1, v186 op_sel_hi:[0,0,0]
	v_mfma_scale_f32_16x16x128_f8f6f4 v[134:137], v[26:33], v[198:205], v[134:137], v1, v186 op_sel_hi:[0,0,0]
	v_mfma_scale_f32_16x16x128_f8f6f4 v[126:129], v[18:25], v[206:213], v[126:129], v1, v186 op_sel_hi:[0,0,0]
	v_mfma_scale_f32_16x16x128_f8f6f4 v[118:121], v[26:33], v[206:213], v[118:121], v1, v186 op_sel_hi:[0,0,0]
	v_mfma_scale_f32_16x16x128_f8f6f4 v[110:113], v[18:25], v[214:221], v[110:113], v1, v186 op_sel_hi:[0,0,0]
	v_mfma_scale_f32_16x16x128_f8f6f4 v[102:105], v[26:33], v[214:221], v[102:105], v1, v186 op_sel_hi:[0,0,0]
	s_setprio 0
	s_setprio 1
	v_mfma_scale_f32_16x16x128_f8f6f4 v[154:157], v[2:9], v[178:185], v[154:157], v1, v186 op_sel_hi:[0,0,0]
	v_mfma_scale_f32_16x16x128_f8f6f4 v[146:149], v[10:17], v[178:185], v[146:149], v1, v186 op_sel_hi:[0,0,0]
	v_mfma_scale_f32_16x16x128_f8f6f4 v[138:141], v[2:9], v[198:205], v[138:141], v1, v186 op_sel_hi:[0,0,0]
	v_mfma_scale_f32_16x16x128_f8f6f4 v[130:133], v[10:17], v[198:205], v[130:133], v1, v186 op_sel_hi:[0,0,0]
	v_mfma_scale_f32_16x16x128_f8f6f4 v[122:125], v[2:9], v[206:213], v[122:125], v1, v186 op_sel_hi:[0,0,0]
	v_mfma_scale_f32_16x16x128_f8f6f4 v[114:117], v[10:17], v[206:213], v[114:117], v1, v186 op_sel_hi:[0,0,0]
	v_mfma_scale_f32_16x16x128_f8f6f4 v[106:109], v[2:9], v[214:221], v[106:109], v1, v186 op_sel_hi:[0,0,0]
	v_mfma_scale_f32_16x16x128_f8f6f4 v[98:101], v[10:17], v[214:221], v[98:101], v1, v186 op_sel_hi:[0,0,0]
.Lcy4_0j:
	s_setprio 0
	s_barrier
	s_add_i32 s56, s41, s30
	s_mov_b32 m0, s56
	ds_read_b128 v[198:201], v195 offset:16384
	ds_read_b128 v[206:209], v195 offset:18432
	ds_read_b128 v[202:205], v196 offset:16384
	ds_read_b128 v[210:213], v196 offset:18432
	ds_read_b128 v[214:217], v195 offset:20480
	ds_read_b128 v[222:225], v195 offset:22528
	ds_read_b128 v[218:221], v196 offset:20480
	ds_read_b128 v[226:229], v196 offset:22528
	global_load_lds_dwordx4 v164, s[22:23]
	s_add_i32 m0, s56, 0x2000
	s_add_u32 s56, s22, 0x40000
	s_addc_u32 s57, s23, 0
	s_add_i32 s58, s42, s30
	global_load_lds_dwordx4 v168, s[22:23]
	s_mov_b32 m0, s58
	s_nop 0
	global_load_lds_dwordx4 v164, s[56:57]
	s_add_i32 m0, s58, 0x2000
	s_nop 0
	global_load_lds_dwordx4 v168, s[56:57]
	s_mov_b32 m0, s19
	s_nop 0
	global_load_lds_dwordx4 v162, s[24:25]
	s_mov_b32 m0, s34
	s_nop 0
	global_load_lds_dwordx4 v166, s[24:25]
	s_waitcnt vmcnt(8)
	s_waitcnt lgkmcnt(0)
	s_barrier
	s_setprio 1
	s_waitcnt lgkmcnt(0)
	s_cmp_eq_u32 s100, 1
	s_cbranch_scc1 .Lcy4_1f
	v_mfma_scale_f32_16x16x128_f8f6f4 v[94:97], v[18:25], v[198:205], v[94:97], v1, v186 op_sel_hi:[0,0,0]
	v_mfma_scale_f32_16x16x128_f8f6f4 v[86:89], v[26:33], v[198:205], v[86:89], v1, v186 op_sel_hi:[0,0,0]
	v_mfma_scale_f32_16x16x128_f8f6f4 v[78:81], v[18:25], v[206:213], v[78:81], v1, v186 op_sel_hi:[0,0,0]
	v_mfma_scale_f32_16x16x128_f8f6f4 v[70:73], v[26:33], v[206:213], v[70:73], v1, v186 op_sel_hi:[0,0,0]
	v_mfma_scale_f32_16x16x128_f8f6f4 v[62:65], v[18:25], v[214:221], v[62:65], v1, v186 op_sel_hi:[0,0,0]
	v_mfma_scale_f32_16x16x128_f8f6f4 v[54:57], v[26:33], v[214:221], v[54:57], v1, v186 op_sel_hi:[0,0,0]
	v_mfma_scale_f32_16x16x128_f8f6f4 v[46:49], v[18:25], v[222:229], v[46:49], v1, v186 op_sel_hi:[0,0,0]
	v_mfma_scale_f32_16x16x128_f8f6f4 v[38:41], v[26:33], v[222:229], v[38:41], v1, v186 op_sel_hi:[0,0,0]
	s_setprio 0
	s_setprio 1
	v_mfma_scale_f32_16x16x128_f8f6f4 v[90:93], v[2:9], v[198:205], v[90:93], v1, v186 op_sel_hi:[0,0,0]
	v_mfma_scale_f32_16x16x128_f8f6f4 v[82:85], v[10:17], v[198:205], v[82:85], v1, v186 op_sel_hi:[0,0,0]
	v_mfma_scale_f32_16x16x128_f8f6f4 v[74:77], v[2:9], v[206:213], v[74:77], v1, v186 op_sel_hi:[0,0,0]
	v_mfma_scale_f32_16x16x128_f8f6f4 v[66:69], v[10:17], v[206:213], v[66:69], v1, v186 op_sel_hi:[0,0,0]
	v_mfma_scale_f32_16x16x128_f8f6f4 v[58:61], v[2:9], v[214:221], v[58:61], v1, v186 op_sel_hi:[0,0,0]
	v_mfma_scale_f32_16x16x128_f8f6f4 v[50:53], v[10:17], v[214:221], v[50:53], v1, v186 op_sel_hi:[0,0,0]
	v_mfma_scale_f32_16x16x128_f8f6f4 v[42:45], v[2:9], v[222:229], v[42:45], v1, v186 op_sel_hi:[0,0,0]
	v_mfma_scale_f32_16x16x128_f8f6f4 v[34:37], v[10:17], v[222:229], v[34:37], v1, v186 op_sel_hi:[0,0,0]
; #define PG8_STAGE(bufoff, gbase, voff) do { _Pragma("unroll") for (int _i = 0; _i < 2; ++_i) \
;         __builtin_amdgcn_global_load_lds((const unsigned*)((const char*)(gbase) + (voff)[_i]), (PG8_LAS unsigned*)(lds + (bufoff) + ldsw + _i * 8192), 16, 0, 0); } while (0)
; #define PG8_LDA(dst, b, h) do { _Pragma("unroll") for (int m = 0; m < 4; ++m) _Pragma("unroll") for (int k = 0; k < 2; ++k) dst[m][k] = *(const PG8_LAS bf16x8*)(lds + PG8_SA(b, h) + aoff + m * 2048 + k * 1024); } while (0)
; #define PG8_LDB(dst, b, h) do { _Pragma("unroll") for (int n = 0; n < 2; ++n) _Pragma("unroll") for (int k = 0; k < 2; ++k) dst[n][k] = *(const PG8_LAS bf16x8*)(lds + PG8_SB(b, h) + boff + n * 2048 + k * 1024); } while (0)
; #define PG8_MMA(ai, bj, At, Bt) do { __builtin_amdgcn_s_setprio(1); _Pragma("unroll") for (int m = 0; m < 4; ++m) _Pragma("unroll") for (int n = 0; n < 2; ++n) _Pragma("unroll") for (int k = 0; k < 2; ++k) \
;         acc[ai][bj][m][n] = __builtin_amdgcn_mfma_f32_16x16x32_bf16(Bt[n][k], At[m][k], acc[ai][bj][m][n], 0, 0, 0); __builtin_amdgcn_s_setprio(0); } while (0)
; #define PG8_WAIT_V(n) asm volatile("s_waitcnt vmcnt(" #n ")" ::: "memory")
; #define PG8_WAIT_L(n) asm volatile("s_waitcnt lgkmcnt(" #n ")" ::: "memory")
; #define PG8_BAR __builtin_amdgcn_s_barrier()
; #define PG8_SCHED __builtin_amdgcn_sched_barrier(0)
; #define PG8_STAGE(bufoff, gbase, voff) do { _Pragma("unroll") for (int _i = 0; _i < 2; ++_i) \
;         __builtin_amdgcn_global_load_lds((const unsigned*)((const char*)(gbase) + (voff)[_i]), (PG8_LAS unsigned*)(lds + (bufoff) + ldsw + _i * 8192), 16, 0, 0); } while (0)
; #define PG8_BAR __builtin_amdgcn_s_barrier()
; template <class Epi, class Sched, bool ALIGN_EPI = false>
; __device__ __forceinline__ void gemm_phase8(PG8_LAS unsigned char* lds, const Gemm g, const Sched& S, const Epi& E) {
;     ...
;             PG8_LDB(B0, 1, 0); PG8_LDB(B1, 1, 1); PG8_SCHED; PG8_LDA(At, 1, 0); PG8_STAGE(PG8_SA(0, 1), a2 + hstepA, voffA);
;             PG8_WAIT_V(8); PG8_WAIT_L(0); PG8_BAR; PG8_MMA(0, 0, At, B0); PG8_MMA(0, 1, At, B1); PG8_BAR; PG8_SCHED;
;             PG8_LDA(At, 1, 1); PG8_STAGE(PG8_SB(1, 0), b3, voffB); PG8_STAGE(PG8_SB(1, 1), b3 + hstepB, voffB); PG8_STAGE(PG8_SA(1, 0), a3, voffA);
;             PG8_WAIT_V(8); PG8_WAIT_L(0); PG8_BAR; PG8_MMA(1, 0, At, B0); PG8_MMA(1, 1, At, B1); PG8_BAR; PG8_SCHED;
;         }
.Lcy4_1j:
	s_setprio 0
	s_barrier
	s_add_i32 s56, 0, 0x18000
	s_add_i32 s57, 0, 0x1c000
	v_add_u32_e32 v6, s56, v187
	v_add_u32_e32 v14, s56, v188
	v_add_u32_e32 v22, s57, v187
	v_add_u32_e32 v30, s57, v188
	ds_read_b128 v[2:5], v6
	ds_read_b128 v[10:13], v6 offset:2048
	ds_read_b128 v[6:9], v14
	ds_read_b128 v[14:17], v14 offset:2048
	ds_read_b128 v[18:21], v22
	ds_read_b128 v[26:29], v22 offset:2048
	ds_read_b128 v[22:25], v30
	ds_read_b128 v[30:33], v30 offset:2048
	s_add_u32 s24, s24, 0x40000
	s_addc_u32 s25, s25, 0
	s_mov_b32 m0, s35
	ds_read_b128 v[198:201], v195 offset:32768
	ds_read_b128 v[206:209], v195 offset:34816
	ds_read_b128 v[202:205], v196 offset:32768
	ds_read_b128 v[210:213], v196 offset:34816
	ds_read_b128 v[214:217], v195 offset:36864
	ds_read_b128 v[222:225], v195 offset:38912
	ds_read_b128 v[218:221], v196 offset:36864
	ds_read_b128 v[226:229], v196 offset:38912
	global_load_lds_dwordx4 v162, s[24:25]
	s_mov_b32 m0, s36
	s_nop 0
	global_load_lds_dwordx4 v166, s[24:25]
	s_waitcnt vmcnt(8)
	s_waitcnt lgkmcnt(0)
	s_barrier
	s_setprio 1
	s_waitcnt lgkmcnt(0)
	v_mfma_scale_f32_16x16x128_f8f6f4 v[158:161], v[2:9], v[198:205], v[158:161], v1, v186 op_sel_hi:[0,0,0]
	v_mfma_scale_f32_16x16x128_f8f6f4 v[150:153], v[10:17], v[198:205], v[150:153], v1, v186 op_sel_hi:[0,0,0]
	v_mfma_scale_f32_16x16x128_f8f6f4 v[142:145], v[2:9], v[206:213], v[142:145], v1, v186 op_sel_hi:[0,0,0]
	v_mfma_scale_f32_16x16x128_f8f6f4 v[134:137], v[10:17], v[206:213], v[134:137], v1, v186 op_sel_hi:[0,0,0]
	v_mfma_scale_f32_16x16x128_f8f6f4 v[126:129], v[2:9], v[214:221], v[126:129], v1, v186 op_sel_hi:[0,0,0]
	v_mfma_scale_f32_16x16x128_f8f6f4 v[118:121], v[10:17], v[214:221], v[118:121], v1, v186 op_sel_hi:[0,0,0]
	v_mfma_scale_f32_16x16x128_f8f6f4 v[110:113], v[2:9], v[222:229], v[110:113], v1, v186 op_sel_hi:[0,0,0]
	v_mfma_scale_f32_16x16x128_f8f6f4 v[102:105], v[10:17], v[222:229], v[102:105], v1, v186 op_sel_hi:[0,0,0]
	s_setprio 0
	s_setprio 1
	v_mfma_scale_f32_16x16x128_f8f6f4 v[154:157], v[18:25], v[198:205], v[154:157], v1, v186 op_sel_hi:[0,0,0]
	v_mfma_scale_f32_16x16x128_f8f6f4 v[146:149], v[26:33], v[198:205], v[146:149], v1, v186 op_sel_hi:[0,0,0]
	v_mfma_scale_f32_16x16x128_f8f6f4 v[138:141], v[18:25], v[206:213], v[138:141], v1, v186 op_sel_hi:[0,0,0]
	v_mfma_scale_f32_16x16x128_f8f6f4 v[130:133], v[26:33], v[206:213], v[130:133], v1, v186 op_sel_hi:[0,0,0]
	v_mfma_scale_f32_16x16x128_f8f6f4 v[122:125], v[18:25], v[214:221], v[122:125], v1, v186 op_sel_hi:[0,0,0]
	v_mfma_scale_f32_16x16x128_f8f6f4 v[114:117], v[26:33], v[214:221], v[114:117], v1, v186 op_sel_hi:[0,0,0]
	v_mfma_scale_f32_16x16x128_f8f6f4 v[106:109], v[18:25], v[222:229], v[106:109], v1, v186 op_sel_hi:[0,0,0]
	v_mfma_scale_f32_16x16x128_f8f6f4 v[98:101], v[26:33], v[222:229], v[98:101], v1, v186 op_sel_hi:[0,0,0]
	s_setprio 0
	s_barrier
	s_add_i32 s101, s56, s30
	s_add_u32 s98, s22, s6
	s_addc_u32 s99, s23, s7
	s_mov_b32 m0, s101
	ds_read_b128 v[198:201], v195 offset:49152
	ds_read_b128 v[206:209], v195 offset:51200
	ds_read_b128 v[202:205], v196 offset:49152
	ds_read_b128 v[210:213], v196 offset:51200
	ds_read_b128 v[214:217], v195 offset:53248
	ds_read_b128 v[222:225], v195 offset:55296
	ds_read_b128 v[218:221], v196 offset:53248
	ds_read_b128 v[226:229], v196 offset:55296
	global_load_lds_dwordx4 v164, s[98:99]
	s_add_i32 m0, s101, 0x2000
	s_add_u32 s22, s22, 0x40080
	s_addc_u32 s23, s23, 0
	s_add_i32 s101, s57, s30
	global_load_lds_dwordx4 v168, s[98:99]
	s_add_u32 s98, s24, s6
	s_addc_u32 s99, s25, s7
	s_sub_u32 s98, s98, 0x40000
	s_subb_u32 s99, s99, 0
	s_mov_b32 m0, s101
	s_nop 0
	global_load_lds_dwordx4 v164, s[22:23]
	s_add_i32 m0, s101, 0x2000
	s_nop 0
	global_load_lds_dwordx4 v168, s[22:23]
	s_mov_b32 m0, s39
	s_nop 0
	global_load_lds_dwordx4 v162, s[98:99]
	s_mov_b32 m0, s40
	s_nop 0
	global_load_lds_dwordx4 v166, s[98:99]
	s_waitcnt vmcnt(8)
	s_waitcnt lgkmcnt(0)
	s_barrier
	s_setprio 1
	s_waitcnt lgkmcnt(0)
	v_mfma_scale_f32_16x16x128_f8f6f4 v[94:97], v[2:9], v[198:205], v[94:97], v1, v186 op_sel_hi:[0,0,0]
	v_mfma_scale_f32_16x16x128_f8f6f4 v[86:89], v[10:17], v[198:205], v[86:89], v1, v186 op_sel_hi:[0,0,0]
	v_mfma_scale_f32_16x16x128_f8f6f4 v[78:81], v[2:9], v[206:213], v[78:81], v1, v186 op_sel_hi:[0,0,0]
	v_mfma_scale_f32_16x16x128_f8f6f4 v[70:73], v[10:17], v[206:213], v[70:73], v1, v186 op_sel_hi:[0,0,0]
	v_mfma_scale_f32_16x16x128_f8f6f4 v[62:65], v[2:9], v[214:221], v[62:65], v1, v186 op_sel_hi:[0,0,0]
	v_mfma_scale_f32_16x16x128_f8f6f4 v[54:57], v[10:17], v[214:221], v[54:57], v1, v186 op_sel_hi:[0,0,0]
	v_mfma_scale_f32_16x16x128_f8f6f4 v[46:49], v[2:9], v[222:229], v[46:49], v1, v186 op_sel_hi:[0,0,0]
	v_mfma_scale_f32_16x16x128_f8f6f4 v[38:41], v[10:17], v[222:229], v[38:41], v1, v186 op_sel_hi:[0,0,0]
	s_setprio 0
	s_setprio 1
	v_mfma_scale_f32_16x16x128_f8f6f4 v[90:93], v[18:25], v[198:205], v[90:93], v1, v186 op_sel_hi:[0,0,0]
	v_mfma_scale_f32_16x16x128_f8f6f4 v[82:85], v[26:33], v[198:205], v[82:85], v1, v186 op_sel_hi:[0,0,0]
	v_mfma_scale_f32_16x16x128_f8f6f4 v[74:77], v[18:25], v[206:213], v[74:77], v1, v186 op_sel_hi:[0,0,0]
	v_mfma_scale_f32_16x16x128_f8f6f4 v[66:69], v[26:33], v[206:213], v[66:69], v1, v186 op_sel_hi:[0,0,0]
	v_mfma_scale_f32_16x16x128_f8f6f4 v[58:61], v[18:25], v[214:221], v[58:61], v1, v186 op_sel_hi:[0,0,0]
	v_mfma_scale_f32_16x16x128_f8f6f4 v[50:53], v[26:33], v[214:221], v[50:53], v1, v186 op_sel_hi:[0,0,0]
	v_mfma_scale_f32_16x16x128_f8f6f4 v[42:45], v[18:25], v[222:229], v[42:45], v1, v186 op_sel_hi:[0,0,0]
	v_mfma_scale_f32_16x16x128_f8f6f4 v[34:37], v[26:33], v[222:229], v[34:37], v1, v186 op_sel_hi:[0,0,0]
	s_setprio 0
	s_barrier
	s_add_i32 s55, s55, 2
	s_add_u32 s20, s20, 0x100
	s_addc_u32 s21, s21, 0
	s_add_u32 s53, s53, 0x100
	s_addc_u32 s54, s54, 0
	s_cmp_gt_u32 s55, 13
	s_cbranch_scc0 .LBB0_1422
	s_and_b64 vcc, exec, s[8:9]
	s_cbranch_vccz .LBB0_1425
	s_barrier
